# outproj's MERGED-panel acquire no longer invalidates L1/L2 (nothing on the XCD read MERGED since the last grid barrier)
# speedup vs baseline: 1.0133x; 1.0133x over previous
.Lop_acqok:
.Lop_acqw:
	s_barrier
	s_lshr_b32 s1, s78, 2
	s_lshl_b32 s1, s1, 7
	s_lshl_b32 s2, s0, 8
	s_mul_i32 s3, s2, 0x800
	s_add_u32 s68, s18, s3
	s_addc_u32 s69, s19, 0
	s_mul_i32 s3, s1, 0x800
	s_add_u32 s70, s80, s3
	s_addc_u32 s71, s81, 0
	s_lshl_b32 s3, s2, 11
	s_lshl_b32 s12, s1, 1
	s_add_u32 s3, s3, s12
	s_add_u32 s74, s24, s3
	s_addc_u32 s75, s25, 0
	s_add_i32 s12, s0, -12
	s_lshr_b32 s12, s12, 2
	s_cmp_lt_u32 s0, 16
	s_cselect_b32 s12, 0, s12
	s_cselect_b32 s14, s52, s54
	s_cselect_b32 s15, s53, s55
	s_mul_i32 s13, s82, 5
	s_add_i32 s12, s12, s13
	s_mul_i32 s12, s12, 0x6000
	s_add_u32 s12, s12, 0x2000
	s_lshl_b32 s13, s1, 2
	s_add_u32 s12, s12, s13
	s_add_u32 s72, s30, s12
	s_addc_u32 s73, s31, 0
	s_and_b32 s12, s0, 15
	s_lshl_b32 s12, s12, 20
	s_add_u32 s12, s12, s13
	s_add_u32 s14, s14, s12
	s_addc_u32 s15, s15, 0
	s_cmp_eq_u32 s82, 0
	s_cselect_b32 s14, s14, s74
	s_cselect_b32 s15, s15, s75
	s_cselect_b32 s38, 64, 32
	s_cselect_b64 vcc, -1, 0
	s_lshl_b32 s39, s38, 1
	s_add_u32 s40, s39, s38
	v_cndmask_b32_e32 v191, v206, v210, vcc
	v_cndmask_b32_e32 v192, v207, v211, vcc
	v_cndmask_b32_e32 v193, v208, v168, vcc
	v_cndmask_b32_e32 v244, v209, v169, vcc
	s_add_u32 m0, s76, 0x0
	s_nop 0
	global_load_lds_dwordx4 v196, s[68:69]
	s_add_u32 m0, s76, 0x2000
	s_nop 0
	global_load_lds_dwordx4 v197, s[68:69]
	s_add_u32 m0, s76, 0x4000
	s_nop 0
	global_load_lds_dwordx4 v198, s[68:69]
	s_add_u32 m0, s76, 0x6000
	s_nop 0
	global_load_lds_dwordx4 v199, s[68:69]
	s_add_u32 m0, s76, 0x8000
	s_nop 0
	global_load_lds_dwordx4 v196, s[70:71]
	s_add_u32 m0, s76, 0xa000
	s_nop 0
	global_load_lds_dwordx4 v197, s[70:71]
	s_add_u32 s68, s68, 0x80
	s_addc_u32 s69, s69, 0
	s_add_u32 s70, s70, 0x80
	s_addc_u32 s71, s71, 0
	s_add_u32 m0, s76, 0xc000
	s_nop 0
	global_load_lds_dwordx4 v196, s[68:69]
	s_add_u32 m0, s76, 0xe000
	s_nop 0
	global_load_lds_dwordx4 v197, s[68:69]
	s_add_u32 m0, s76, 0x10000
	s_nop 0
	global_load_lds_dwordx4 v198, s[68:69]
	s_add_u32 m0, s76, 0x12000
	s_nop 0
	global_load_lds_dwordx4 v199, s[68:69]
	s_add_u32 m0, s76, 0x14000
	s_nop 0
	global_load_lds_dwordx4 v196, s[70:71]
	s_add_u32 m0, s76, 0x16000
	s_nop 0
	global_load_lds_dwordx4 v197, s[70:71]
	s_add_u32 s68, s68, 0x80
	s_addc_u32 s69, s69, 0
	s_add_u32 s70, s70, 0x80
	s_addc_u32 s71, s71, 0
	s_waitcnt vmcnt(6)
	s_barrier
	s_cmp_ge_u32 s76, 0x1000
	s_cbranch_scc1 .Lop_streamB
	v_add_u32_e32 v204, 0x0, v200
	v_add_u32_e32 v205, 0x0, v202
	ds_read_b128 v[130:133], v204 offset:0
	ds_read_b128 v[134:137], v204 offset:2048
	ds_read_b128 v[138:141], v204 offset:4096
	ds_read_b128 v[142:145], v204 offset:6144
	ds_read_b128 v[146:149], v205 offset:0
	ds_read_b128 v[150:153], v205 offset:2048
	ds_read_b128 v[154:157], v205 offset:4096
	ds_read_b128 v[158:161], v205 offset:6144
	v_add_u32_e32 v204, 0x0, v201
	v_add_u32_e32 v205, 0x0, v203
	ds_read_b128 v[212:215], v204 offset:0
	ds_read_b128 v[216:219], v204 offset:2048
	ds_read_b128 v[220:223], v204 offset:4096
	ds_read_b128 v[224:227], v204 offset:6144
	ds_read_b128 v[228:231], v205 offset:0
	ds_read_b128 v[232:235], v205 offset:2048
	ds_read_b128 v[236:239], v205 offset:4096
	ds_read_b128 v[240:243], v205 offset:6144
	s_add_u32 m0, s76, 0x18000
	s_nop 0
	global_load_lds_dwordx4 v196, s[68:69]
	s_add_u32 m0, s76, 0x1a000
	s_nop 0
	global_load_lds_dwordx4 v197, s[68:69]
	s_add_u32 m0, s76, 0x1c000
	s_nop 0
	global_load_lds_dwordx4 v198, s[68:69]
	s_add_u32 m0, s76, 0x1e000
	s_nop 0
	global_load_lds_dwordx4 v199, s[68:69]
	s_add_u32 m0, s76, 0x20000
	s_nop 0
	global_load_lds_dwordx4 v196, s[70:71]
	s_add_u32 m0, s76, 0x22000
	s_nop 0
	global_load_lds_dwordx4 v197, s[70:71]
	s_add_u32 s68, s68, 0x80
	s_addc_u32 s69, s69, 0
	s_add_u32 s70, s70, 0x80
	s_addc_u32 s71, s71, 0
	global_load_dwordx4 v[174:177], v190, s[72:73] offset:0
	global_load_dwordx4 v[178:181], v190, s[72:73] offset:64
	s_waitcnt lgkmcnt(0)
	s_barrier
	v_mfma_f32_16x16x32_bf16 v[2:5], v[146:149], v[130:133], 0
	v_mfma_f32_16x16x32_bf16 v[6:9], v[150:153], v[130:133], 0
	v_mfma_f32_16x16x32_bf16 v[10:13], v[154:157], v[130:133], 0
	v_mfma_f32_16x16x32_bf16 v[14:17], v[158:161], v[130:133], 0
	v_mfma_f32_16x16x32_bf16 v[18:21], v[146:149], v[134:137], 0
	v_mfma_f32_16x16x32_bf16 v[22:25], v[150:153], v[134:137], 0
	v_mfma_f32_16x16x32_bf16 v[26:29], v[154:157], v[134:137], 0
	v_mfma_f32_16x16x32_bf16 v[30:33], v[158:161], v[134:137], 0
	v_mfma_f32_16x16x32_bf16 v[34:37], v[146:149], v[138:141], 0
	v_mfma_f32_16x16x32_bf16 v[38:41], v[150:153], v[138:141], 0
	v_mfma_f32_16x16x32_bf16 v[42:45], v[154:157], v[138:141], 0
	v_mfma_f32_16x16x32_bf16 v[46:49], v[158:161], v[138:141], 0
	v_mfma_f32_16x16x32_bf16 v[50:53], v[146:149], v[142:145], 0
	v_mfma_f32_16x16x32_bf16 v[54:57], v[150:153], v[142:145], 0
	v_mfma_f32_16x16x32_bf16 v[58:61], v[154:157], v[142:145], 0
	v_mfma_f32_16x16x32_bf16 v[62:65], v[158:161], v[142:145], 0
	v_mfma_f32_16x16x32_bf16 v[2:5], v[228:231], v[212:215], v[2:5]
	v_mfma_f32_16x16x32_bf16 v[6:9], v[232:235], v[212:215], v[6:9]
	v_mfma_f32_16x16x32_bf16 v[10:13], v[236:239], v[212:215], v[10:13]
	v_mfma_f32_16x16x32_bf16 v[14:17], v[240:243], v[212:215], v[14:17]
	v_mfma_f32_16x16x32_bf16 v[18:21], v[228:231], v[216:219], v[18:21]
	v_mfma_f32_16x16x32_bf16 v[22:25], v[232:235], v[216:219], v[22:25]
	v_mfma_f32_16x16x32_bf16 v[26:29], v[236:239], v[216:219], v[26:29]
	v_mfma_f32_16x16x32_bf16 v[30:33], v[240:243], v[216:219], v[30:33]
	v_mfma_f32_16x16x32_bf16 v[34:37], v[228:231], v[220:223], v[34:37]
	v_mfma_f32_16x16x32_bf16 v[38:41], v[232:235], v[220:223], v[38:41]
	v_mfma_f32_16x16x32_bf16 v[42:45], v[236:239], v[220:223], v[42:45]
	v_mfma_f32_16x16x32_bf16 v[46:49], v[240:243], v[220:223], v[46:49]
	v_mfma_f32_16x16x32_bf16 v[50:53], v[228:231], v[224:227], v[50:53]
	v_mfma_f32_16x16x32_bf16 v[54:57], v[232:235], v[224:227], v[54:57]
	v_mfma_f32_16x16x32_bf16 v[58:61], v[236:239], v[224:227], v[58:61]
	v_mfma_f32_16x16x32_bf16 v[62:65], v[240:243], v[224:227], v[62:65]
	s_waitcnt vmcnt(8)
	s_barrier
	v_add_u32_e32 v204, 0xc000, v200
	v_add_u32_e32 v205, 0xc000, v202
	ds_read_b128 v[130:133], v204 offset:0
	ds_read_b128 v[134:137], v204 offset:2048
	ds_read_b128 v[138:141], v204 offset:4096
	ds_read_b128 v[142:145], v204 offset:6144
	ds_read_b128 v[146:149], v205 offset:0
	ds_read_b128 v[150:153], v205 offset:2048
	ds_read_b128 v[154:157], v205 offset:4096
	ds_read_b128 v[158:161], v205 offset:6144
	v_add_u32_e32 v204, 0xc000, v201
	v_add_u32_e32 v205, 0xc000, v203
	ds_read_b128 v[212:215], v204 offset:0
	ds_read_b128 v[216:219], v204 offset:2048
	ds_read_b128 v[220:223], v204 offset:4096
	ds_read_b128 v[224:227], v204 offset:6144
	ds_read_b128 v[228:231], v205 offset:0
	ds_read_b128 v[232:235], v205 offset:2048
	ds_read_b128 v[236:239], v205 offset:4096
	ds_read_b128 v[240:243], v205 offset:6144
	s_add_u32 m0, s76, 0x0
	s_nop 0
	global_load_lds_dwordx4 v196, s[68:69]
	s_add_u32 m0, s76, 0x2000
	s_nop 0
	global_load_lds_dwordx4 v197, s[68:69]
	s_add_u32 m0, s76, 0x4000
	s_nop 0
	global_load_lds_dwordx4 v198, s[68:69]
	s_add_u32 m0, s76, 0x6000
	s_nop 0
	global_load_lds_dwordx4 v199, s[68:69]
	s_add_u32 m0, s76, 0x8000
	s_nop 0
	global_load_lds_dwordx4 v196, s[70:71]
	s_add_u32 m0, s76, 0xa000
	s_nop 0
	global_load_lds_dwordx4 v197, s[70:71]
	s_add_u32 s68, s68, 0x80
	s_addc_u32 s69, s69, 0
	s_add_u32 s70, s70, 0x80
	s_addc_u32 s71, s71, 0
	global_load_dwordx4 v[182:185], v190, s[72:73] offset:128
	global_load_dwordx4 v[186:189], v190, s[72:73] offset:192
	s_waitcnt lgkmcnt(0)
	s_barrier
	v_mfma_f32_16x16x32_bf16 v[2:5], v[146:149], v[130:133], v[2:5]
	v_mfma_f32_16x16x32_bf16 v[6:9], v[150:153], v[130:133], v[6:9]
	v_mfma_f32_16x16x32_bf16 v[10:13], v[154:157], v[130:133], v[10:13]
	v_mfma_f32_16x16x32_bf16 v[14:17], v[158:161], v[130:133], v[14:17]
	v_mfma_f32_16x16x32_bf16 v[18:21], v[146:149], v[134:137], v[18:21]
	v_mfma_f32_16x16x32_bf16 v[22:25], v[150:153], v[134:137], v[22:25]
	v_mfma_f32_16x16x32_bf16 v[26:29], v[154:157], v[134:137], v[26:29]
	v_mfma_f32_16x16x32_bf16 v[30:33], v[158:161], v[134:137], v[30:33]
	v_mfma_f32_16x16x32_bf16 v[34:37], v[146:149], v[138:141], v[34:37]
	v_mfma_f32_16x16x32_bf16 v[38:41], v[150:153], v[138:141], v[38:41]
	v_mfma_f32_16x16x32_bf16 v[42:45], v[154:157], v[138:141], v[42:45]
	v_mfma_f32_16x16x32_bf16 v[46:49], v[158:161], v[138:141], v[46:49]
	v_mfma_f32_16x16x32_bf16 v[50:53], v[146:149], v[142:145], v[50:53]
	v_mfma_f32_16x16x32_bf16 v[54:57], v[150:153], v[142:145], v[54:57]
	v_mfma_f32_16x16x32_bf16 v[58:61], v[154:157], v[142:145], v[58:61]
	v_mfma_f32_16x16x32_bf16 v[62:65], v[158:161], v[142:145], v[62:65]
	v_mfma_f32_16x16x32_bf16 v[2:5], v[228:231], v[212:215], v[2:5]
	v_mfma_f32_16x16x32_bf16 v[6:9], v[232:235], v[212:215], v[6:9]
	v_mfma_f32_16x16x32_bf16 v[10:13], v[236:239], v[212:215], v[10:13]
	v_mfma_f32_16x16x32_bf16 v[14:17], v[240:243], v[212:215], v[14:17]
	v_mfma_f32_16x16x32_bf16 v[18:21], v[228:231], v[216:219], v[18:21]
	v_mfma_f32_16x16x32_bf16 v[22:25], v[232:235], v[216:219], v[22:25]
	v_mfma_f32_16x16x32_bf16 v[26:29], v[236:239], v[216:219], v[26:29]
	v_mfma_f32_16x16x32_bf16 v[30:33], v[240:243], v[216:219], v[30:33]
	v_mfma_f32_16x16x32_bf16 v[34:37], v[228:231], v[220:223], v[34:37]
	v_mfma_f32_16x16x32_bf16 v[38:41], v[232:235], v[220:223], v[38:41]
	v_mfma_f32_16x16x32_bf16 v[42:45], v[236:239], v[220:223], v[42:45]
	v_mfma_f32_16x16x32_bf16 v[46:49], v[240:243], v[220:223], v[46:49]
	v_mfma_f32_16x16x32_bf16 v[50:53], v[228:231], v[224:227], v[50:53]
	v_mfma_f32_16x16x32_bf16 v[54:57], v[232:235], v[224:227], v[54:57]
	v_mfma_f32_16x16x32_bf16 v[58:61], v[236:239], v[224:227], v[58:61]
	v_mfma_f32_16x16x32_bf16 v[62:65], v[240:243], v[224:227], v[62:65]
	s_waitcnt vmcnt(10)
	s_barrier
	v_add_u32_e32 v204, 0x18000, v200
	v_add_u32_e32 v205, 0x18000, v202
	ds_read_b128 v[130:133], v204 offset:0
	ds_read_b128 v[134:137], v204 offset:2048
	ds_read_b128 v[138:141], v204 offset:4096
	ds_read_b128 v[142:145], v204 offset:6144
	ds_read_b128 v[146:149], v205 offset:0
	ds_read_b128 v[150:153], v205 offset:2048
	ds_read_b128 v[154:157], v205 offset:4096
	ds_read_b128 v[158:161], v205 offset:6144
	v_add_u32_e32 v204, 0x18000, v201
	v_add_u32_e32 v205, 0x18000, v203
	ds_read_b128 v[212:215], v204 offset:0
	ds_read_b128 v[216:219], v204 offset:2048
	ds_read_b128 v[220:223], v204 offset:4096
	ds_read_b128 v[224:227], v204 offset:6144
	ds_read_b128 v[228:231], v205 offset:0
	ds_read_b128 v[232:235], v205 offset:2048
	ds_read_b128 v[236:239], v205 offset:4096
	ds_read_b128 v[240:243], v205 offset:6144
	s_add_u32 m0, s76, 0xc000
	s_nop 0
	global_load_lds_dwordx4 v196, s[68:69]
	s_add_u32 m0, s76, 0xe000
	s_nop 0
	global_load_lds_dwordx4 v197, s[68:69]
	s_add_u32 m0, s76, 0x10000
	s_nop 0
	global_load_lds_dwordx4 v198, s[68:69]
	s_add_u32 m0, s76, 0x12000
	s_nop 0
	global_load_lds_dwordx4 v199, s[68:69]
	s_add_u32 m0, s76, 0x14000
	s_nop 0
	global_load_lds_dwordx4 v196, s[70:71]
	s_add_u32 m0, s76, 0x16000
	s_nop 0
	global_load_lds_dwordx4 v197, s[70:71]
	s_add_u32 s68, s68, 0x80
	s_addc_u32 s69, s69, 0
	s_add_u32 s70, s70, 0x80
	s_addc_u32 s71, s71, 0
	global_load_dwordx4 v[66:69], v191, s[14:15]
	v_add_u32_e32 v170, s38, v191
	global_load_dwordx4 v[70:73], v170, s[14:15]
	s_waitcnt lgkmcnt(0)
	s_barrier
	v_mfma_f32_16x16x32_bf16 v[2:5], v[146:149], v[130:133], v[2:5]
	v_mfma_f32_16x16x32_bf16 v[6:9], v[150:153], v[130:133], v[6:9]
	v_mfma_f32_16x16x32_bf16 v[10:13], v[154:157], v[130:133], v[10:13]
	v_mfma_f32_16x16x32_bf16 v[14:17], v[158:161], v[130:133], v[14:17]
	v_mfma_f32_16x16x32_bf16 v[18:21], v[146:149], v[134:137], v[18:21]
	v_mfma_f32_16x16x32_bf16 v[22:25], v[150:153], v[134:137], v[22:25]
	v_mfma_f32_16x16x32_bf16 v[26:29], v[154:157], v[134:137], v[26:29]
	v_mfma_f32_16x16x32_bf16 v[30:33], v[158:161], v[134:137], v[30:33]
	v_mfma_f32_16x16x32_bf16 v[34:37], v[146:149], v[138:141], v[34:37]
	v_mfma_f32_16x16x32_bf16 v[38:41], v[150:153], v[138:141], v[38:41]
	v_mfma_f32_16x16x32_bf16 v[42:45], v[154:157], v[138:141], v[42:45]
	v_mfma_f32_16x16x32_bf16 v[46:49], v[158:161], v[138:141], v[46:49]
	v_mfma_f32_16x16x32_bf16 v[50:53], v[146:149], v[142:145], v[50:53]
	v_mfma_f32_16x16x32_bf16 v[54:57], v[150:153], v[142:145], v[54:57]
	v_mfma_f32_16x16x32_bf16 v[58:61], v[154:157], v[142:145], v[58:61]
	v_mfma_f32_16x16x32_bf16 v[62:65], v[158:161], v[142:145], v[62:65]
	v_mfma_f32_16x16x32_bf16 v[2:5], v[228:231], v[212:215], v[2:5]
	v_mfma_f32_16x16x32_bf16 v[6:9], v[232:235], v[212:215], v[6:9]
	v_mfma_f32_16x16x32_bf16 v[10:13], v[236:239], v[212:215], v[10:13]
	v_mfma_f32_16x16x32_bf16 v[14:17], v[240:243], v[212:215], v[14:17]
	v_mfma_f32_16x16x32_bf16 v[18:21], v[228:231], v[216:219], v[18:21]
	v_mfma_f32_16x16x32_bf16 v[22:25], v[232:235], v[216:219], v[22:25]
	v_mfma_f32_16x16x32_bf16 v[26:29], v[236:239], v[216:219], v[26:29]
	v_mfma_f32_16x16x32_bf16 v[30:33], v[240:243], v[216:219], v[30:33]
	v_mfma_f32_16x16x32_bf16 v[34:37], v[228:231], v[220:223], v[34:37]
	v_mfma_f32_16x16x32_bf16 v[38:41], v[232:235], v[220:223], v[38:41]
	v_mfma_f32_16x16x32_bf16 v[42:45], v[236:239], v[220:223], v[42:45]
	v_mfma_f32_16x16x32_bf16 v[46:49], v[240:243], v[220:223], v[46:49]
	v_mfma_f32_16x16x32_bf16 v[50:53], v[228:231], v[224:227], v[50:53]
	v_mfma_f32_16x16x32_bf16 v[54:57], v[232:235], v[224:227], v[54:57]
	v_mfma_f32_16x16x32_bf16 v[58:61], v[236:239], v[224:227], v[58:61]
	v_mfma_f32_16x16x32_bf16 v[62:65], v[240:243], v[224:227], v[62:65]
	s_waitcnt vmcnt(10)
	s_barrier
	v_add_u32_e32 v204, 0x0, v200
	v_add_u32_e32 v205, 0x0, v202
	ds_read_b128 v[130:133], v204 offset:0
	ds_read_b128 v[134:137], v204 offset:2048
	ds_read_b128 v[138:141], v204 offset:4096
	ds_read_b128 v[142:145], v204 offset:6144
	ds_read_b128 v[146:149], v205 offset:0
	ds_read_b128 v[150:153], v205 offset:2048
	ds_read_b128 v[154:157], v205 offset:4096
	ds_read_b128 v[158:161], v205 offset:6144
	v_add_u32_e32 v204, 0x0, v201
	v_add_u32_e32 v205, 0x0, v203
	ds_read_b128 v[212:215], v204 offset:0
	ds_read_b128 v[216:219], v204 offset:2048
	ds_read_b128 v[220:223], v204 offset:4096
	ds_read_b128 v[224:227], v204 offset:6144
	ds_read_b128 v[228:231], v205 offset:0
	ds_read_b128 v[232:235], v205 offset:2048
	ds_read_b128 v[236:239], v205 offset:4096
	ds_read_b128 v[240:243], v205 offset:6144
	s_add_u32 m0, s76, 0x18000
	s_nop 0
	global_load_lds_dwordx4 v196, s[68:69]
	s_add_u32 m0, s76, 0x1a000
	s_nop 0
	global_load_lds_dwordx4 v197, s[68:69]
	s_add_u32 m0, s76, 0x1c000
	s_nop 0
	global_load_lds_dwordx4 v198, s[68:69]
	s_add_u32 m0, s76, 0x1e000
	s_nop 0
	global_load_lds_dwordx4 v199, s[68:69]
	s_add_u32 m0, s76, 0x20000
	s_nop 0
	global_load_lds_dwordx4 v196, s[70:71]
	s_add_u32 m0, s76, 0x22000
	s_nop 0
	global_load_lds_dwordx4 v197, s[70:71]
	s_add_u32 s68, s68, 0x80
	s_addc_u32 s69, s69, 0
	s_add_u32 s70, s70, 0x80
	s_addc_u32 s71, s71, 0
	v_add_u32_e32 v170, s39, v191
	global_load_dwordx4 v[74:77], v170, s[14:15]
	v_add_u32_e32 v170, s40, v191
	global_load_dwordx4 v[78:81], v170, s[14:15]
	s_waitcnt lgkmcnt(0)
	s_barrier
	v_mfma_f32_16x16x32_bf16 v[2:5], v[146:149], v[130:133], v[2:5]
	v_mfma_f32_16x16x32_bf16 v[6:9], v[150:153], v[130:133], v[6:9]
	v_mfma_f32_16x16x32_bf16 v[10:13], v[154:157], v[130:133], v[10:13]
	v_mfma_f32_16x16x32_bf16 v[14:17], v[158:161], v[130:133], v[14:17]
	v_mfma_f32_16x16x32_bf16 v[18:21], v[146:149], v[134:137], v[18:21]
	v_mfma_f32_16x16x32_bf16 v[22:25], v[150:153], v[134:137], v[22:25]
	v_mfma_f32_16x16x32_bf16 v[26:29], v[154:157], v[134:137], v[26:29]
	v_mfma_f32_16x16x32_bf16 v[30:33], v[158:161], v[134:137], v[30:33]
	v_mfma_f32_16x16x32_bf16 v[34:37], v[146:149], v[138:141], v[34:37]
	v_mfma_f32_16x16x32_bf16 v[38:41], v[150:153], v[138:141], v[38:41]
	v_mfma_f32_16x16x32_bf16 v[42:45], v[154:157], v[138:141], v[42:45]
	v_mfma_f32_16x16x32_bf16 v[46:49], v[158:161], v[138:141], v[46:49]
	v_mfma_f32_16x16x32_bf16 v[50:53], v[146:149], v[142:145], v[50:53]
	v_mfma_f32_16x16x32_bf16 v[54:57], v[150:153], v[142:145], v[54:57]
	v_mfma_f32_16x16x32_bf16 v[58:61], v[154:157], v[142:145], v[58:61]
	v_mfma_f32_16x16x32_bf16 v[62:65], v[158:161], v[142:145], v[62:65]
	v_mfma_f32_16x16x32_bf16 v[2:5], v[228:231], v[212:215], v[2:5]
	v_mfma_f32_16x16x32_bf16 v[6:9], v[232:235], v[212:215], v[6:9]
	v_mfma_f32_16x16x32_bf16 v[10:13], v[236:239], v[212:215], v[10:13]
	v_mfma_f32_16x16x32_bf16 v[14:17], v[240:243], v[212:215], v[14:17]
	v_mfma_f32_16x16x32_bf16 v[18:21], v[228:231], v[216:219], v[18:21]
	v_mfma_f32_16x16x32_bf16 v[22:25], v[232:235], v[216:219], v[22:25]
	v_mfma_f32_16x16x32_bf16 v[26:29], v[236:239], v[216:219], v[26:29]
	v_mfma_f32_16x16x32_bf16 v[30:33], v[240:243], v[216:219], v[30:33]
	v_mfma_f32_16x16x32_bf16 v[34:37], v[228:231], v[220:223], v[34:37]
	v_mfma_f32_16x16x32_bf16 v[38:41], v[232:235], v[220:223], v[38:41]
	v_mfma_f32_16x16x32_bf16 v[42:45], v[236:239], v[220:223], v[42:45]
	v_mfma_f32_16x16x32_bf16 v[46:49], v[240:243], v[220:223], v[46:49]
	v_mfma_f32_16x16x32_bf16 v[50:53], v[228:231], v[224:227], v[50:53]
	v_mfma_f32_16x16x32_bf16 v[54:57], v[232:235], v[224:227], v[54:57]
	v_mfma_f32_16x16x32_bf16 v[58:61], v[236:239], v[224:227], v[58:61]
	v_mfma_f32_16x16x32_bf16 v[62:65], v[240:243], v[224:227], v[62:65]
	s_waitcnt vmcnt(10)
	s_barrier
	v_add_u32_e32 v204, 0xc000, v200
	v_add_u32_e32 v205, 0xc000, v202
	ds_read_b128 v[130:133], v204 offset:0
	ds_read_b128 v[134:137], v204 offset:2048
	ds_read_b128 v[138:141], v204 offset:4096
	ds_read_b128 v[142:145], v204 offset:6144
	ds_read_b128 v[146:149], v205 offset:0
	ds_read_b128 v[150:153], v205 offset:2048
	ds_read_b128 v[154:157], v205 offset:4096
	ds_read_b128 v[158:161], v205 offset:6144
	v_add_u32_e32 v204, 0xc000, v201
	v_add_u32_e32 v205, 0xc000, v203
	ds_read_b128 v[212:215], v204 offset:0
	ds_read_b128 v[216:219], v204 offset:2048
	ds_read_b128 v[220:223], v204 offset:4096
	ds_read_b128 v[224:227], v204 offset:6144
	ds_read_b128 v[228:231], v205 offset:0
	ds_read_b128 v[232:235], v205 offset:2048
	ds_read_b128 v[236:239], v205 offset:4096
	ds_read_b128 v[240:243], v205 offset:6144
	s_add_u32 m0, s76, 0x0
	s_nop 0
	global_load_lds_dwordx4 v196, s[68:69]
	s_add_u32 m0, s76, 0x2000
	s_nop 0
	global_load_lds_dwordx4 v197, s[68:69]
	s_add_u32 m0, s76, 0x4000
	s_nop 0
	global_load_lds_dwordx4 v198, s[68:69]
	s_add_u32 m0, s76, 0x6000
	s_nop 0
	global_load_lds_dwordx4 v199, s[68:69]
	s_add_u32 m0, s76, 0x8000
	s_nop 0
	global_load_lds_dwordx4 v196, s[70:71]
	s_add_u32 m0, s76, 0xa000
	s_nop 0
	global_load_lds_dwordx4 v197, s[70:71]
	s_add_u32 s68, s68, 0x80
	s_addc_u32 s69, s69, 0
	s_add_u32 s70, s70, 0x80
	s_addc_u32 s71, s71, 0
	global_load_dwordx4 v[82:85], v192, s[14:15]
	v_add_u32_e32 v170, s38, v192
	global_load_dwordx4 v[86:89], v170, s[14:15]
	s_waitcnt lgkmcnt(0)
	s_barrier
	v_mfma_f32_16x16x32_bf16 v[2:5], v[146:149], v[130:133], v[2:5]
	v_mfma_f32_16x16x32_bf16 v[6:9], v[150:153], v[130:133], v[6:9]
	v_mfma_f32_16x16x32_bf16 v[10:13], v[154:157], v[130:133], v[10:13]
	v_mfma_f32_16x16x32_bf16 v[14:17], v[158:161], v[130:133], v[14:17]
	v_mfma_f32_16x16x32_bf16 v[18:21], v[146:149], v[134:137], v[18:21]
	v_mfma_f32_16x16x32_bf16 v[22:25], v[150:153], v[134:137], v[22:25]
	v_mfma_f32_16x16x32_bf16 v[26:29], v[154:157], v[134:137], v[26:29]
	v_mfma_f32_16x16x32_bf16 v[30:33], v[158:161], v[134:137], v[30:33]
	v_mfma_f32_16x16x32_bf16 v[34:37], v[146:149], v[138:141], v[34:37]
	v_mfma_f32_16x16x32_bf16 v[38:41], v[150:153], v[138:141], v[38:41]
	v_mfma_f32_16x16x32_bf16 v[42:45], v[154:157], v[138:141], v[42:45]
	v_mfma_f32_16x16x32_bf16 v[46:49], v[158:161], v[138:141], v[46:49]
	v_mfma_f32_16x16x32_bf16 v[50:53], v[146:149], v[142:145], v[50:53]
	v_mfma_f32_16x16x32_bf16 v[54:57], v[150:153], v[142:145], v[54:57]
	v_mfma_f32_16x16x32_bf16 v[58:61], v[154:157], v[142:145], v[58:61]
	v_mfma_f32_16x16x32_bf16 v[62:65], v[158:161], v[142:145], v[62:65]
	v_mfma_f32_16x16x32_bf16 v[2:5], v[228:231], v[212:215], v[2:5]
	v_mfma_f32_16x16x32_bf16 v[6:9], v[232:235], v[212:215], v[6:9]
	v_mfma_f32_16x16x32_bf16 v[10:13], v[236:239], v[212:215], v[10:13]
	v_mfma_f32_16x16x32_bf16 v[14:17], v[240:243], v[212:215], v[14:17]
	v_mfma_f32_16x16x32_bf16 v[18:21], v[228:231], v[216:219], v[18:21]
	v_mfma_f32_16x16x32_bf16 v[22:25], v[232:235], v[216:219], v[22:25]
	v_mfma_f32_16x16x32_bf16 v[26:29], v[236:239], v[216:219], v[26:29]
	v_mfma_f32_16x16x32_bf16 v[30:33], v[240:243], v[216:219], v[30:33]
	v_mfma_f32_16x16x32_bf16 v[34:37], v[228:231], v[220:223], v[34:37]
	v_mfma_f32_16x16x32_bf16 v[38:41], v[232:235], v[220:223], v[38:41]
	v_mfma_f32_16x16x32_bf16 v[42:45], v[236:239], v[220:223], v[42:45]
	v_mfma_f32_16x16x32_bf16 v[46:49], v[240:243], v[220:223], v[46:49]
	v_mfma_f32_16x16x32_bf16 v[50:53], v[228:231], v[224:227], v[50:53]
	v_mfma_f32_16x16x32_bf16 v[54:57], v[232:235], v[224:227], v[54:57]
	v_mfma_f32_16x16x32_bf16 v[58:61], v[236:239], v[224:227], v[58:61]
	v_mfma_f32_16x16x32_bf16 v[62:65], v[240:243], v[224:227], v[62:65]
	s_waitcnt vmcnt(10)
	s_barrier
	v_add_u32_e32 v204, 0x18000, v200
	v_add_u32_e32 v205, 0x18000, v202
	ds_read_b128 v[130:133], v204 offset:0
	ds_read_b128 v[134:137], v204 offset:2048
	ds_read_b128 v[138:141], v204 offset:4096
	ds_read_b128 v[142:145], v204 offset:6144
	ds_read_b128 v[146:149], v205 offset:0
	ds_read_b128 v[150:153], v205 offset:2048
	ds_read_b128 v[154:157], v205 offset:4096
	ds_read_b128 v[158:161], v205 offset:6144
	v_add_u32_e32 v204, 0x18000, v201
	v_add_u32_e32 v205, 0x18000, v203
	ds_read_b128 v[212:215], v204 offset:0
	ds_read_b128 v[216:219], v204 offset:2048
	ds_read_b128 v[220:223], v204 offset:4096
	ds_read_b128 v[224:227], v204 offset:6144
	ds_read_b128 v[228:231], v205 offset:0
	ds_read_b128 v[232:235], v205 offset:2048
	ds_read_b128 v[236:239], v205 offset:4096
	ds_read_b128 v[240:243], v205 offset:6144
	s_add_u32 m0, s76, 0xc000
	s_nop 0
	global_load_lds_dwordx4 v196, s[68:69]
	s_add_u32 m0, s76, 0xe000
	s_nop 0
	global_load_lds_dwordx4 v197, s[68:69]
	s_add_u32 m0, s76, 0x10000
	s_nop 0
	global_load_lds_dwordx4 v198, s[68:69]
	s_add_u32 m0, s76, 0x12000
	s_nop 0
	global_load_lds_dwordx4 v199, s[68:69]
	s_add_u32 m0, s76, 0x14000
	s_nop 0
	global_load_lds_dwordx4 v196, s[70:71]
	s_add_u32 m0, s76, 0x16000
	s_nop 0
	global_load_lds_dwordx4 v197, s[70:71]
	s_add_u32 s68, s68, 0x80
	s_addc_u32 s69, s69, 0
	s_add_u32 s70, s70, 0x80
	s_addc_u32 s71, s71, 0
	v_add_u32_e32 v170, s39, v192
	global_load_dwordx4 v[90:93], v170, s[14:15]
	v_add_u32_e32 v170, s40, v192
	global_load_dwordx4 v[94:97], v170, s[14:15]
	s_waitcnt lgkmcnt(0)
	s_barrier
	v_mfma_f32_16x16x32_bf16 v[2:5], v[146:149], v[130:133], v[2:5]
	v_mfma_f32_16x16x32_bf16 v[6:9], v[150:153], v[130:133], v[6:9]
	v_mfma_f32_16x16x32_bf16 v[10:13], v[154:157], v[130:133], v[10:13]
	v_mfma_f32_16x16x32_bf16 v[14:17], v[158:161], v[130:133], v[14:17]
	v_mfma_f32_16x16x32_bf16 v[18:21], v[146:149], v[134:137], v[18:21]
	v_mfma_f32_16x16x32_bf16 v[22:25], v[150:153], v[134:137], v[22:25]
	v_mfma_f32_16x16x32_bf16 v[26:29], v[154:157], v[134:137], v[26:29]
	v_mfma_f32_16x16x32_bf16 v[30:33], v[158:161], v[134:137], v[30:33]
	v_mfma_f32_16x16x32_bf16 v[34:37], v[146:149], v[138:141], v[34:37]
	v_mfma_f32_16x16x32_bf16 v[38:41], v[150:153], v[138:141], v[38:41]
	v_mfma_f32_16x16x32_bf16 v[42:45], v[154:157], v[138:141], v[42:45]
	v_mfma_f32_16x16x32_bf16 v[46:49], v[158:161], v[138:141], v[46:49]
	v_mfma_f32_16x16x32_bf16 v[50:53], v[146:149], v[142:145], v[50:53]
	v_mfma_f32_16x16x32_bf16 v[54:57], v[150:153], v[142:145], v[54:57]
	v_mfma_f32_16x16x32_bf16 v[58:61], v[154:157], v[142:145], v[58:61]
	v_mfma_f32_16x16x32_bf16 v[62:65], v[158:161], v[142:145], v[62:65]
	v_mfma_f32_16x16x32_bf16 v[2:5], v[228:231], v[212:215], v[2:5]
	v_mfma_f32_16x16x32_bf16 v[6:9], v[232:235], v[212:215], v[6:9]
	v_mfma_f32_16x16x32_bf16 v[10:13], v[236:239], v[212:215], v[10:13]
	v_mfma_f32_16x16x32_bf16 v[14:17], v[240:243], v[212:215], v[14:17]
	v_mfma_f32_16x16x32_bf16 v[18:21], v[228:231], v[216:219], v[18:21]
	v_mfma_f32_16x16x32_bf16 v[22:25], v[232:235], v[216:219], v[22:25]
	v_mfma_f32_16x16x32_bf16 v[26:29], v[236:239], v[216:219], v[26:29]
	v_mfma_f32_16x16x32_bf16 v[30:33], v[240:243], v[216:219], v[30:33]
	v_mfma_f32_16x16x32_bf16 v[34:37], v[228:231], v[220:223], v[34:37]
	v_mfma_f32_16x16x32_bf16 v[38:41], v[232:235], v[220:223], v[38:41]
	v_mfma_f32_16x16x32_bf16 v[42:45], v[236:239], v[220:223], v[42:45]
	v_mfma_f32_16x16x32_bf16 v[46:49], v[240:243], v[220:223], v[46:49]
	v_mfma_f32_16x16x32_bf16 v[50:53], v[228:231], v[224:227], v[50:53]
	v_mfma_f32_16x16x32_bf16 v[54:57], v[232:235], v[224:227], v[54:57]
	v_mfma_f32_16x16x32_bf16 v[58:61], v[236:239], v[224:227], v[58:61]
	v_mfma_f32_16x16x32_bf16 v[62:65], v[240:243], v[224:227], v[62:65]
	s_waitcnt vmcnt(10)
	s_barrier
	v_add_u32_e32 v204, 0x0, v200
	v_add_u32_e32 v205, 0x0, v202
	ds_read_b128 v[130:133], v204 offset:0
	ds_read_b128 v[134:137], v204 offset:2048
	ds_read_b128 v[138:141], v204 offset:4096
	ds_read_b128 v[142:145], v204 offset:6144
	ds_read_b128 v[146:149], v205 offset:0
	ds_read_b128 v[150:153], v205 offset:2048
	ds_read_b128 v[154:157], v205 offset:4096
	ds_read_b128 v[158:161], v205 offset:6144
	v_add_u32_e32 v204, 0x0, v201
	v_add_u32_e32 v205, 0x0, v203
	ds_read_b128 v[212:215], v204 offset:0
	ds_read_b128 v[216:219], v204 offset:2048
	ds_read_b128 v[220:223], v204 offset:4096
	ds_read_b128 v[224:227], v204 offset:6144
	ds_read_b128 v[228:231], v205 offset:0
	ds_read_b128 v[232:235], v205 offset:2048
	ds_read_b128 v[236:239], v205 offset:4096
	ds_read_b128 v[240:243], v205 offset:6144
	s_add_u32 m0, s76, 0x18000
	s_nop 0
	global_load_lds_dwordx4 v196, s[68:69]
	s_add_u32 m0, s76, 0x1a000
	s_nop 0
	global_load_lds_dwordx4 v197, s[68:69]
	s_add_u32 m0, s76, 0x1c000
	s_nop 0
	global_load_lds_dwordx4 v198, s[68:69]
	s_add_u32 m0, s76, 0x1e000
	s_nop 0
	global_load_lds_dwordx4 v199, s[68:69]
	s_add_u32 m0, s76, 0x20000
	s_nop 0
	global_load_lds_dwordx4 v196, s[70:71]
	s_add_u32 m0, s76, 0x22000
	s_nop 0
	global_load_lds_dwordx4 v197, s[70:71]
	s_add_u32 s68, s68, 0x80
	s_addc_u32 s69, s69, 0
	s_add_u32 s70, s70, 0x80
	s_addc_u32 s71, s71, 0
	global_load_dwordx4 v[98:101], v193, s[14:15]
	v_add_u32_e32 v170, s38, v193
	global_load_dwordx4 v[102:105], v170, s[14:15]
	s_waitcnt lgkmcnt(0)
	s_barrier
	v_mfma_f32_16x16x32_bf16 v[2:5], v[146:149], v[130:133], v[2:5]
	v_mfma_f32_16x16x32_bf16 v[6:9], v[150:153], v[130:133], v[6:9]
	v_mfma_f32_16x16x32_bf16 v[10:13], v[154:157], v[130:133], v[10:13]
	v_mfma_f32_16x16x32_bf16 v[14:17], v[158:161], v[130:133], v[14:17]
	v_mfma_f32_16x16x32_bf16 v[18:21], v[146:149], v[134:137], v[18:21]
	v_mfma_f32_16x16x32_bf16 v[22:25], v[150:153], v[134:137], v[22:25]
	v_mfma_f32_16x16x32_bf16 v[26:29], v[154:157], v[134:137], v[26:29]
	v_mfma_f32_16x16x32_bf16 v[30:33], v[158:161], v[134:137], v[30:33]
	v_mfma_f32_16x16x32_bf16 v[34:37], v[146:149], v[138:141], v[34:37]
	v_mfma_f32_16x16x32_bf16 v[38:41], v[150:153], v[138:141], v[38:41]
	v_mfma_f32_16x16x32_bf16 v[42:45], v[154:157], v[138:141], v[42:45]
	v_mfma_f32_16x16x32_bf16 v[46:49], v[158:161], v[138:141], v[46:49]
	v_mfma_f32_16x16x32_bf16 v[50:53], v[146:149], v[142:145], v[50:53]
	v_mfma_f32_16x16x32_bf16 v[54:57], v[150:153], v[142:145], v[54:57]
	v_mfma_f32_16x16x32_bf16 v[58:61], v[154:157], v[142:145], v[58:61]
	v_mfma_f32_16x16x32_bf16 v[62:65], v[158:161], v[142:145], v[62:65]
	v_mfma_f32_16x16x32_bf16 v[2:5], v[228:231], v[212:215], v[2:5]
	v_mfma_f32_16x16x32_bf16 v[6:9], v[232:235], v[212:215], v[6:9]
	v_mfma_f32_16x16x32_bf16 v[10:13], v[236:239], v[212:215], v[10:13]
	v_mfma_f32_16x16x32_bf16 v[14:17], v[240:243], v[212:215], v[14:17]
	v_mfma_f32_16x16x32_bf16 v[18:21], v[228:231], v[216:219], v[18:21]
	v_mfma_f32_16x16x32_bf16 v[22:25], v[232:235], v[216:219], v[22:25]
	v_mfma_f32_16x16x32_bf16 v[26:29], v[236:239], v[216:219], v[26:29]
	v_mfma_f32_16x16x32_bf16 v[30:33], v[240:243], v[216:219], v[30:33]
	v_mfma_f32_16x16x32_bf16 v[34:37], v[228:231], v[220:223], v[34:37]
	v_mfma_f32_16x16x32_bf16 v[38:41], v[232:235], v[220:223], v[38:41]
	v_mfma_f32_16x16x32_bf16 v[42:45], v[236:239], v[220:223], v[42:45]
	v_mfma_f32_16x16x32_bf16 v[46:49], v[240:243], v[220:223], v[46:49]
	v_mfma_f32_16x16x32_bf16 v[50:53], v[228:231], v[224:227], v[50:53]
	v_mfma_f32_16x16x32_bf16 v[54:57], v[232:235], v[224:227], v[54:57]
	v_mfma_f32_16x16x32_bf16 v[58:61], v[236:239], v[224:227], v[58:61]
	v_mfma_f32_16x16x32_bf16 v[62:65], v[240:243], v[224:227], v[62:65]
	s_waitcnt vmcnt(10)
	s_barrier
	v_add_u32_e32 v204, 0xc000, v200
	v_add_u32_e32 v205, 0xc000, v202
	ds_read_b128 v[130:133], v204 offset:0
	ds_read_b128 v[134:137], v204 offset:2048
	ds_read_b128 v[138:141], v204 offset:4096
	ds_read_b128 v[142:145], v204 offset:6144
	ds_read_b128 v[146:149], v205 offset:0
	ds_read_b128 v[150:153], v205 offset:2048
	ds_read_b128 v[154:157], v205 offset:4096
	ds_read_b128 v[158:161], v205 offset:6144
	v_add_u32_e32 v204, 0xc000, v201
	v_add_u32_e32 v205, 0xc000, v203
	ds_read_b128 v[212:215], v204 offset:0
	ds_read_b128 v[216:219], v204 offset:2048
	ds_read_b128 v[220:223], v204 offset:4096
	ds_read_b128 v[224:227], v204 offset:6144
	ds_read_b128 v[228:231], v205 offset:0
	ds_read_b128 v[232:235], v205 offset:2048
	ds_read_b128 v[236:239], v205 offset:4096
	ds_read_b128 v[240:243], v205 offset:6144
	s_add_u32 m0, s76, 0x0
	s_nop 0
	global_load_lds_dwordx4 v196, s[68:69]
	s_add_u32 m0, s76, 0x2000
	s_nop 0
	global_load_lds_dwordx4 v197, s[68:69]
	s_add_u32 m0, s76, 0x4000
	s_nop 0
	global_load_lds_dwordx4 v198, s[68:69]
	s_add_u32 m0, s76, 0x6000
	s_nop 0
	global_load_lds_dwordx4 v199, s[68:69]
	s_add_u32 m0, s76, 0x8000
	s_nop 0
	global_load_lds_dwordx4 v196, s[70:71]
	s_add_u32 m0, s76, 0xa000
	s_nop 0
	global_load_lds_dwordx4 v197, s[70:71]
	s_add_u32 s68, s68, 0x80
	s_addc_u32 s69, s69, 0
	s_add_u32 s70, s70, 0x80
	s_addc_u32 s71, s71, 0
	v_add_u32_e32 v170, s39, v193
	global_load_dwordx4 v[106:109], v170, s[14:15]
	v_add_u32_e32 v170, s40, v193
	global_load_dwordx4 v[110:113], v170, s[14:15]
	s_waitcnt lgkmcnt(0)
	s_barrier
	v_mfma_f32_16x16x32_bf16 v[2:5], v[146:149], v[130:133], v[2:5]
	v_mfma_f32_16x16x32_bf16 v[6:9], v[150:153], v[130:133], v[6:9]
	v_mfma_f32_16x16x32_bf16 v[10:13], v[154:157], v[130:133], v[10:13]
	v_mfma_f32_16x16x32_bf16 v[14:17], v[158:161], v[130:133], v[14:17]
	v_mfma_f32_16x16x32_bf16 v[18:21], v[146:149], v[134:137], v[18:21]
	v_mfma_f32_16x16x32_bf16 v[22:25], v[150:153], v[134:137], v[22:25]
	v_mfma_f32_16x16x32_bf16 v[26:29], v[154:157], v[134:137], v[26:29]
	v_mfma_f32_16x16x32_bf16 v[30:33], v[158:161], v[134:137], v[30:33]
	v_mfma_f32_16x16x32_bf16 v[34:37], v[146:149], v[138:141], v[34:37]
	v_mfma_f32_16x16x32_bf16 v[38:41], v[150:153], v[138:141], v[38:41]
	v_mfma_f32_16x16x32_bf16 v[42:45], v[154:157], v[138:141], v[42:45]
	v_mfma_f32_16x16x32_bf16 v[46:49], v[158:161], v[138:141], v[46:49]
	v_mfma_f32_16x16x32_bf16 v[50:53], v[146:149], v[142:145], v[50:53]
	v_mfma_f32_16x16x32_bf16 v[54:57], v[150:153], v[142:145], v[54:57]
	v_mfma_f32_16x16x32_bf16 v[58:61], v[154:157], v[142:145], v[58:61]
	v_mfma_f32_16x16x32_bf16 v[62:65], v[158:161], v[142:145], v[62:65]
	v_mfma_f32_16x16x32_bf16 v[2:5], v[228:231], v[212:215], v[2:5]
	v_mfma_f32_16x16x32_bf16 v[6:9], v[232:235], v[212:215], v[6:9]
	v_mfma_f32_16x16x32_bf16 v[10:13], v[236:239], v[212:215], v[10:13]
	v_mfma_f32_16x16x32_bf16 v[14:17], v[240:243], v[212:215], v[14:17]
	v_mfma_f32_16x16x32_bf16 v[18:21], v[228:231], v[216:219], v[18:21]
	v_mfma_f32_16x16x32_bf16 v[22:25], v[232:235], v[216:219], v[22:25]
	v_mfma_f32_16x16x32_bf16 v[26:29], v[236:239], v[216:219], v[26:29]
	v_mfma_f32_16x16x32_bf16 v[30:33], v[240:243], v[216:219], v[30:33]
	v_mfma_f32_16x16x32_bf16 v[34:37], v[228:231], v[220:223], v[34:37]
	v_mfma_f32_16x16x32_bf16 v[38:41], v[232:235], v[220:223], v[38:41]
	v_mfma_f32_16x16x32_bf16 v[42:45], v[236:239], v[220:223], v[42:45]
	v_mfma_f32_16x16x32_bf16 v[46:49], v[240:243], v[220:223], v[46:49]
	v_mfma_f32_16x16x32_bf16 v[50:53], v[228:231], v[224:227], v[50:53]
	v_mfma_f32_16x16x32_bf16 v[54:57], v[232:235], v[224:227], v[54:57]
	v_mfma_f32_16x16x32_bf16 v[58:61], v[236:239], v[224:227], v[58:61]
	v_mfma_f32_16x16x32_bf16 v[62:65], v[240:243], v[224:227], v[62:65]
	s_waitcnt vmcnt(10)
	s_barrier
	v_add_u32_e32 v204, 0x18000, v200
	v_add_u32_e32 v205, 0x18000, v202
	ds_read_b128 v[130:133], v204 offset:0
	ds_read_b128 v[134:137], v204 offset:2048
	ds_read_b128 v[138:141], v204 offset:4096
	ds_read_b128 v[142:145], v204 offset:6144
	ds_read_b128 v[146:149], v205 offset:0
	ds_read_b128 v[150:153], v205 offset:2048
	ds_read_b128 v[154:157], v205 offset:4096
	ds_read_b128 v[158:161], v205 offset:6144
	v_add_u32_e32 v204, 0x18000, v201
	v_add_u32_e32 v205, 0x18000, v203
	ds_read_b128 v[212:215], v204 offset:0
	ds_read_b128 v[216:219], v204 offset:2048
	ds_read_b128 v[220:223], v204 offset:4096
	ds_read_b128 v[224:227], v204 offset:6144
	ds_read_b128 v[228:231], v205 offset:0
	ds_read_b128 v[232:235], v205 offset:2048
	ds_read_b128 v[236:239], v205 offset:4096
	ds_read_b128 v[240:243], v205 offset:6144
	s_add_u32 m0, s76, 0xc000
	s_nop 0
	global_load_lds_dwordx4 v196, s[68:69]
	s_add_u32 m0, s76, 0xe000
	s_nop 0
	global_load_lds_dwordx4 v197, s[68:69]
	s_add_u32 m0, s76, 0x10000
	s_nop 0
	global_load_lds_dwordx4 v198, s[68:69]
	s_add_u32 m0, s76, 0x12000
	s_nop 0
	global_load_lds_dwordx4 v199, s[68:69]
	s_add_u32 m0, s76, 0x14000
	s_nop 0
	global_load_lds_dwordx4 v196, s[70:71]
	s_add_u32 m0, s76, 0x16000
	s_nop 0
	global_load_lds_dwordx4 v197, s[70:71]
	s_add_u32 s68, s68, 0x80
	s_addc_u32 s69, s69, 0
	s_add_u32 s70, s70, 0x80
	s_addc_u32 s71, s71, 0
	global_load_dwordx4 v[114:117], v244, s[14:15]
	v_add_u32_e32 v170, s38, v244
	global_load_dwordx4 v[118:121], v170, s[14:15]
	s_waitcnt lgkmcnt(0)
	s_barrier
	v_mfma_f32_16x16x32_bf16 v[2:5], v[146:149], v[130:133], v[2:5]
	v_mfma_f32_16x16x32_bf16 v[6:9], v[150:153], v[130:133], v[6:9]
	v_mfma_f32_16x16x32_bf16 v[10:13], v[154:157], v[130:133], v[10:13]
	v_mfma_f32_16x16x32_bf16 v[14:17], v[158:161], v[130:133], v[14:17]
	v_mfma_f32_16x16x32_bf16 v[18:21], v[146:149], v[134:137], v[18:21]
	v_mfma_f32_16x16x32_bf16 v[22:25], v[150:153], v[134:137], v[22:25]
	v_mfma_f32_16x16x32_bf16 v[26:29], v[154:157], v[134:137], v[26:29]
	v_mfma_f32_16x16x32_bf16 v[30:33], v[158:161], v[134:137], v[30:33]
	v_mfma_f32_16x16x32_bf16 v[34:37], v[146:149], v[138:141], v[34:37]
	v_mfma_f32_16x16x32_bf16 v[38:41], v[150:153], v[138:141], v[38:41]
	v_mfma_f32_16x16x32_bf16 v[42:45], v[154:157], v[138:141], v[42:45]
	v_mfma_f32_16x16x32_bf16 v[46:49], v[158:161], v[138:141], v[46:49]
	v_mfma_f32_16x16x32_bf16 v[50:53], v[146:149], v[142:145], v[50:53]
	v_mfma_f32_16x16x32_bf16 v[54:57], v[150:153], v[142:145], v[54:57]
	v_mfma_f32_16x16x32_bf16 v[58:61], v[154:157], v[142:145], v[58:61]
	v_mfma_f32_16x16x32_bf16 v[62:65], v[158:161], v[142:145], v[62:65]
	v_mfma_f32_16x16x32_bf16 v[2:5], v[228:231], v[212:215], v[2:5]
	v_mfma_f32_16x16x32_bf16 v[6:9], v[232:235], v[212:215], v[6:9]
	v_mfma_f32_16x16x32_bf16 v[10:13], v[236:239], v[212:215], v[10:13]
	v_mfma_f32_16x16x32_bf16 v[14:17], v[240:243], v[212:215], v[14:17]
	v_mfma_f32_16x16x32_bf16 v[18:21], v[228:231], v[216:219], v[18:21]
	v_mfma_f32_16x16x32_bf16 v[22:25], v[232:235], v[216:219], v[22:25]
	v_mfma_f32_16x16x32_bf16 v[26:29], v[236:239], v[216:219], v[26:29]
	v_mfma_f32_16x16x32_bf16 v[30:33], v[240:243], v[216:219], v[30:33]
	v_mfma_f32_16x16x32_bf16 v[34:37], v[228:231], v[220:223], v[34:37]
	v_mfma_f32_16x16x32_bf16 v[38:41], v[232:235], v[220:223], v[38:41]
	v_mfma_f32_16x16x32_bf16 v[42:45], v[236:239], v[220:223], v[42:45]
	v_mfma_f32_16x16x32_bf16 v[46:49], v[240:243], v[220:223], v[46:49]
	v_mfma_f32_16x16x32_bf16 v[50:53], v[228:231], v[224:227], v[50:53]
	v_mfma_f32_16x16x32_bf16 v[54:57], v[232:235], v[224:227], v[54:57]
	v_mfma_f32_16x16x32_bf16 v[58:61], v[236:239], v[224:227], v[58:61]
	v_mfma_f32_16x16x32_bf16 v[62:65], v[240:243], v[224:227], v[62:65]
	s_waitcnt vmcnt(10)
	s_barrier
	v_add_u32_e32 v204, 0x0, v200
	v_add_u32_e32 v205, 0x0, v202
	ds_read_b128 v[130:133], v204 offset:0
	ds_read_b128 v[134:137], v204 offset:2048
	ds_read_b128 v[138:141], v204 offset:4096
	ds_read_b128 v[142:145], v204 offset:6144
	ds_read_b128 v[146:149], v205 offset:0
	ds_read_b128 v[150:153], v205 offset:2048
	ds_read_b128 v[154:157], v205 offset:4096
	ds_read_b128 v[158:161], v205 offset:6144
	v_add_u32_e32 v204, 0x0, v201
	v_add_u32_e32 v205, 0x0, v203
	ds_read_b128 v[212:215], v204 offset:0
	ds_read_b128 v[216:219], v204 offset:2048
	ds_read_b128 v[220:223], v204 offset:4096
	ds_read_b128 v[224:227], v204 offset:6144
	ds_read_b128 v[228:231], v205 offset:0
	ds_read_b128 v[232:235], v205 offset:2048
	ds_read_b128 v[236:239], v205 offset:4096
	ds_read_b128 v[240:243], v205 offset:6144
	s_add_u32 m0, s76, 0x18000
	s_nop 0
	global_load_lds_dwordx4 v196, s[68:69]
	s_add_u32 m0, s76, 0x1a000
	s_nop 0
	global_load_lds_dwordx4 v197, s[68:69]
	s_add_u32 m0, s76, 0x1c000
	s_nop 0
	global_load_lds_dwordx4 v198, s[68:69]
	s_add_u32 m0, s76, 0x1e000
	s_nop 0
	global_load_lds_dwordx4 v199, s[68:69]
	s_add_u32 m0, s76, 0x20000
	s_nop 0
	global_load_lds_dwordx4 v196, s[70:71]
	s_add_u32 m0, s76, 0x22000
	s_nop 0
	global_load_lds_dwordx4 v197, s[70:71]
	s_add_u32 s68, s68, 0x80
	s_addc_u32 s69, s69, 0
	s_add_u32 s70, s70, 0x80
	s_addc_u32 s71, s71, 0
	v_add_u32_e32 v170, s39, v244
	global_load_dwordx4 v[122:125], v170, s[14:15]
	v_add_u32_e32 v170, s40, v244
	global_load_dwordx4 v[126:129], v170, s[14:15]
	s_waitcnt lgkmcnt(0)
	s_barrier
	v_mfma_f32_16x16x32_bf16 v[2:5], v[146:149], v[130:133], v[2:5]
	v_mfma_f32_16x16x32_bf16 v[6:9], v[150:153], v[130:133], v[6:9]
	v_mfma_f32_16x16x32_bf16 v[10:13], v[154:157], v[130:133], v[10:13]
	v_mfma_f32_16x16x32_bf16 v[14:17], v[158:161], v[130:133], v[14:17]
	v_mfma_f32_16x16x32_bf16 v[18:21], v[146:149], v[134:137], v[18:21]
	v_mfma_f32_16x16x32_bf16 v[22:25], v[150:153], v[134:137], v[22:25]
	v_mfma_f32_16x16x32_bf16 v[26:29], v[154:157], v[134:137], v[26:29]
	v_mfma_f32_16x16x32_bf16 v[30:33], v[158:161], v[134:137], v[30:33]
	v_mfma_f32_16x16x32_bf16 v[34:37], v[146:149], v[138:141], v[34:37]
	v_mfma_f32_16x16x32_bf16 v[38:41], v[150:153], v[138:141], v[38:41]
	v_mfma_f32_16x16x32_bf16 v[42:45], v[154:157], v[138:141], v[42:45]
	v_mfma_f32_16x16x32_bf16 v[46:49], v[158:161], v[138:141], v[46:49]
	v_mfma_f32_16x16x32_bf16 v[50:53], v[146:149], v[142:145], v[50:53]
	v_mfma_f32_16x16x32_bf16 v[54:57], v[150:153], v[142:145], v[54:57]
	v_mfma_f32_16x16x32_bf16 v[58:61], v[154:157], v[142:145], v[58:61]
	v_mfma_f32_16x16x32_bf16 v[62:65], v[158:161], v[142:145], v[62:65]
	v_mfma_f32_16x16x32_bf16 v[2:5], v[228:231], v[212:215], v[2:5]
	v_mfma_f32_16x16x32_bf16 v[6:9], v[232:235], v[212:215], v[6:9]
	v_mfma_f32_16x16x32_bf16 v[10:13], v[236:239], v[212:215], v[10:13]
	v_mfma_f32_16x16x32_bf16 v[14:17], v[240:243], v[212:215], v[14:17]
	v_mfma_f32_16x16x32_bf16 v[18:21], v[228:231], v[216:219], v[18:21]
	v_mfma_f32_16x16x32_bf16 v[22:25], v[232:235], v[216:219], v[22:25]
	v_mfma_f32_16x16x32_bf16 v[26:29], v[236:239], v[216:219], v[26:29]
	v_mfma_f32_16x16x32_bf16 v[30:33], v[240:243], v[216:219], v[30:33]
	v_mfma_f32_16x16x32_bf16 v[34:37], v[228:231], v[220:223], v[34:37]
	v_mfma_f32_16x16x32_bf16 v[38:41], v[232:235], v[220:223], v[38:41]
	v_mfma_f32_16x16x32_bf16 v[42:45], v[236:239], v[220:223], v[42:45]
	v_mfma_f32_16x16x32_bf16 v[46:49], v[240:243], v[220:223], v[46:49]
	v_mfma_f32_16x16x32_bf16 v[50:53], v[228:231], v[224:227], v[50:53]
	v_mfma_f32_16x16x32_bf16 v[54:57], v[232:235], v[224:227], v[54:57]
	v_mfma_f32_16x16x32_bf16 v[58:61], v[236:239], v[224:227], v[58:61]
	v_mfma_f32_16x16x32_bf16 v[62:65], v[240:243], v[224:227], v[62:65]
	s_waitcnt vmcnt(10)
	s_barrier
	v_add_u32_e32 v204, 0xc000, v200
	v_add_u32_e32 v205, 0xc000, v202
	ds_read_b128 v[130:133], v204 offset:0
	ds_read_b128 v[134:137], v204 offset:2048
	ds_read_b128 v[138:141], v204 offset:4096
	ds_read_b128 v[142:145], v204 offset:6144
	ds_read_b128 v[146:149], v205 offset:0
	ds_read_b128 v[150:153], v205 offset:2048
	ds_read_b128 v[154:157], v205 offset:4096
	ds_read_b128 v[158:161], v205 offset:6144
	v_add_u32_e32 v204, 0xc000, v201
	v_add_u32_e32 v205, 0xc000, v203
	ds_read_b128 v[212:215], v204 offset:0
	ds_read_b128 v[216:219], v204 offset:2048
	ds_read_b128 v[220:223], v204 offset:4096
	ds_read_b128 v[224:227], v204 offset:6144
	ds_read_b128 v[228:231], v205 offset:0
	ds_read_b128 v[232:235], v205 offset:2048
	ds_read_b128 v[236:239], v205 offset:4096
	ds_read_b128 v[240:243], v205 offset:6144
	s_add_u32 m0, s76, 0x0
	s_nop 0
	global_load_lds_dwordx4 v196, s[68:69]
	s_add_u32 m0, s76, 0x2000
	s_nop 0
	global_load_lds_dwordx4 v197, s[68:69]
	s_add_u32 m0, s76, 0x4000
	s_nop 0
	global_load_lds_dwordx4 v198, s[68:69]
	s_add_u32 m0, s76, 0x6000
	s_nop 0
	global_load_lds_dwordx4 v199, s[68:69]
	s_add_u32 m0, s76, 0x8000
	s_nop 0
	global_load_lds_dwordx4 v196, s[70:71]
	s_add_u32 m0, s76, 0xa000
	s_nop 0
	global_load_lds_dwordx4 v197, s[70:71]
	s_add_u32 s68, s68, 0x80
	s_addc_u32 s69, s69, 0
	s_add_u32 s70, s70, 0x80
	s_addc_u32 s71, s71, 0
	s_waitcnt lgkmcnt(0)
	s_barrier
	v_mfma_f32_16x16x32_bf16 v[2:5], v[146:149], v[130:133], v[2:5]
	v_mfma_f32_16x16x32_bf16 v[6:9], v[150:153], v[130:133], v[6:9]
	v_mfma_f32_16x16x32_bf16 v[10:13], v[154:157], v[130:133], v[10:13]
	v_mfma_f32_16x16x32_bf16 v[14:17], v[158:161], v[130:133], v[14:17]
	v_mfma_f32_16x16x32_bf16 v[18:21], v[146:149], v[134:137], v[18:21]
	v_mfma_f32_16x16x32_bf16 v[22:25], v[150:153], v[134:137], v[22:25]
	v_mfma_f32_16x16x32_bf16 v[26:29], v[154:157], v[134:137], v[26:29]
	v_mfma_f32_16x16x32_bf16 v[30:33], v[158:161], v[134:137], v[30:33]
	v_mfma_f32_16x16x32_bf16 v[34:37], v[146:149], v[138:141], v[34:37]
	v_mfma_f32_16x16x32_bf16 v[38:41], v[150:153], v[138:141], v[38:41]
	v_mfma_f32_16x16x32_bf16 v[42:45], v[154:157], v[138:141], v[42:45]
	v_mfma_f32_16x16x32_bf16 v[46:49], v[158:161], v[138:141], v[46:49]
	v_mfma_f32_16x16x32_bf16 v[50:53], v[146:149], v[142:145], v[50:53]
	v_mfma_f32_16x16x32_bf16 v[54:57], v[150:153], v[142:145], v[54:57]
	v_mfma_f32_16x16x32_bf16 v[58:61], v[154:157], v[142:145], v[58:61]
	v_mfma_f32_16x16x32_bf16 v[62:65], v[158:161], v[142:145], v[62:65]
	v_mfma_f32_16x16x32_bf16 v[2:5], v[228:231], v[212:215], v[2:5]
	v_mfma_f32_16x16x32_bf16 v[6:9], v[232:235], v[212:215], v[6:9]
	v_mfma_f32_16x16x32_bf16 v[10:13], v[236:239], v[212:215], v[10:13]
	v_mfma_f32_16x16x32_bf16 v[14:17], v[240:243], v[212:215], v[14:17]
	v_mfma_f32_16x16x32_bf16 v[18:21], v[228:231], v[216:219], v[18:21]
	v_mfma_f32_16x16x32_bf16 v[22:25], v[232:235], v[216:219], v[22:25]
	v_mfma_f32_16x16x32_bf16 v[26:29], v[236:239], v[216:219], v[26:29]
	v_mfma_f32_16x16x32_bf16 v[30:33], v[240:243], v[216:219], v[30:33]
	v_mfma_f32_16x16x32_bf16 v[34:37], v[228:231], v[220:223], v[34:37]
	v_mfma_f32_16x16x32_bf16 v[38:41], v[232:235], v[220:223], v[38:41]
	v_mfma_f32_16x16x32_bf16 v[42:45], v[236:239], v[220:223], v[42:45]
	v_mfma_f32_16x16x32_bf16 v[46:49], v[240:243], v[220:223], v[46:49]
	v_mfma_f32_16x16x32_bf16 v[50:53], v[228:231], v[224:227], v[50:53]
	v_mfma_f32_16x16x32_bf16 v[54:57], v[232:235], v[224:227], v[54:57]
	v_mfma_f32_16x16x32_bf16 v[58:61], v[236:239], v[224:227], v[58:61]
	v_mfma_f32_16x16x32_bf16 v[62:65], v[240:243], v[224:227], v[62:65]
	s_waitcnt vmcnt(8)
	s_barrier
	v_add_u32_e32 v204, 0x18000, v200
	v_add_u32_e32 v205, 0x18000, v202
	ds_read_b128 v[130:133], v204 offset:0
	ds_read_b128 v[134:137], v204 offset:2048
	ds_read_b128 v[138:141], v204 offset:4096
	ds_read_b128 v[142:145], v204 offset:6144
	ds_read_b128 v[146:149], v205 offset:0
	ds_read_b128 v[150:153], v205 offset:2048
	ds_read_b128 v[154:157], v205 offset:4096
	ds_read_b128 v[158:161], v205 offset:6144
	v_add_u32_e32 v204, 0x18000, v201
	v_add_u32_e32 v205, 0x18000, v203
	ds_read_b128 v[212:215], v204 offset:0
	ds_read_b128 v[216:219], v204 offset:2048
	ds_read_b128 v[220:223], v204 offset:4096
	ds_read_b128 v[224:227], v204 offset:6144
	ds_read_b128 v[228:231], v205 offset:0
	ds_read_b128 v[232:235], v205 offset:2048
	ds_read_b128 v[236:239], v205 offset:4096
	ds_read_b128 v[240:243], v205 offset:6144
	s_add_u32 m0, s76, 0xc000
	s_nop 0
	global_load_lds_dwordx4 v196, s[68:69]
	s_add_u32 m0, s76, 0xe000
	s_nop 0
	global_load_lds_dwordx4 v197, s[68:69]
	s_add_u32 m0, s76, 0x10000
	s_nop 0
	global_load_lds_dwordx4 v198, s[68:69]
	s_add_u32 m0, s76, 0x12000
	s_nop 0
	global_load_lds_dwordx4 v199, s[68:69]
	s_add_u32 m0, s76, 0x14000
	s_nop 0
	global_load_lds_dwordx4 v196, s[70:71]
	s_add_u32 m0, s76, 0x16000
	s_nop 0
	global_load_lds_dwordx4 v197, s[70:71]
	s_add_u32 s68, s68, 0x80
	s_addc_u32 s69, s69, 0
	s_add_u32 s70, s70, 0x80
	s_addc_u32 s71, s71, 0
	s_waitcnt lgkmcnt(0)
	s_barrier
	v_mfma_f32_16x16x32_bf16 v[2:5], v[146:149], v[130:133], v[2:5]
	v_mfma_f32_16x16x32_bf16 v[6:9], v[150:153], v[130:133], v[6:9]
	v_mfma_f32_16x16x32_bf16 v[10:13], v[154:157], v[130:133], v[10:13]
	v_mfma_f32_16x16x32_bf16 v[14:17], v[158:161], v[130:133], v[14:17]
	v_mfma_f32_16x16x32_bf16 v[18:21], v[146:149], v[134:137], v[18:21]
	v_mfma_f32_16x16x32_bf16 v[22:25], v[150:153], v[134:137], v[22:25]
	v_mfma_f32_16x16x32_bf16 v[26:29], v[154:157], v[134:137], v[26:29]
	v_mfma_f32_16x16x32_bf16 v[30:33], v[158:161], v[134:137], v[30:33]
	v_mfma_f32_16x16x32_bf16 v[34:37], v[146:149], v[138:141], v[34:37]
	v_mfma_f32_16x16x32_bf16 v[38:41], v[150:153], v[138:141], v[38:41]
	v_mfma_f32_16x16x32_bf16 v[42:45], v[154:157], v[138:141], v[42:45]
	v_mfma_f32_16x16x32_bf16 v[46:49], v[158:161], v[138:141], v[46:49]
	v_mfma_f32_16x16x32_bf16 v[50:53], v[146:149], v[142:145], v[50:53]
	v_mfma_f32_16x16x32_bf16 v[54:57], v[150:153], v[142:145], v[54:57]
	v_mfma_f32_16x16x32_bf16 v[58:61], v[154:157], v[142:145], v[58:61]
	v_mfma_f32_16x16x32_bf16 v[62:65], v[158:161], v[142:145], v[62:65]
	v_mfma_f32_16x16x32_bf16 v[2:5], v[228:231], v[212:215], v[2:5]
	v_mfma_f32_16x16x32_bf16 v[6:9], v[232:235], v[212:215], v[6:9]
	v_mfma_f32_16x16x32_bf16 v[10:13], v[236:239], v[212:215], v[10:13]
	v_mfma_f32_16x16x32_bf16 v[14:17], v[240:243], v[212:215], v[14:17]
	v_mfma_f32_16x16x32_bf16 v[18:21], v[228:231], v[216:219], v[18:21]
	v_mfma_f32_16x16x32_bf16 v[22:25], v[232:235], v[216:219], v[22:25]
	v_mfma_f32_16x16x32_bf16 v[26:29], v[236:239], v[216:219], v[26:29]
	v_mfma_f32_16x16x32_bf16 v[30:33], v[240:243], v[216:219], v[30:33]
	v_mfma_f32_16x16x32_bf16 v[34:37], v[228:231], v[220:223], v[34:37]
	v_mfma_f32_16x16x32_bf16 v[38:41], v[232:235], v[220:223], v[38:41]
	v_mfma_f32_16x16x32_bf16 v[42:45], v[236:239], v[220:223], v[42:45]
	v_mfma_f32_16x16x32_bf16 v[46:49], v[240:243], v[220:223], v[46:49]
	v_mfma_f32_16x16x32_bf16 v[50:53], v[228:231], v[224:227], v[50:53]
	v_mfma_f32_16x16x32_bf16 v[54:57], v[232:235], v[224:227], v[54:57]
	v_mfma_f32_16x16x32_bf16 v[58:61], v[236:239], v[224:227], v[58:61]
	v_mfma_f32_16x16x32_bf16 v[62:65], v[240:243], v[224:227], v[62:65]
	s_waitcnt vmcnt(6)
	s_barrier
	v_add_u32_e32 v204, 0x0, v200
	v_add_u32_e32 v205, 0x0, v202
	ds_read_b128 v[130:133], v204 offset:0
	ds_read_b128 v[134:137], v204 offset:2048
	ds_read_b128 v[138:141], v204 offset:4096
	ds_read_b128 v[142:145], v204 offset:6144
	ds_read_b128 v[146:149], v205 offset:0
	ds_read_b128 v[150:153], v205 offset:2048
	ds_read_b128 v[154:157], v205 offset:4096
	ds_read_b128 v[158:161], v205 offset:6144
	v_add_u32_e32 v204, 0x0, v201
	v_add_u32_e32 v205, 0x0, v203
	ds_read_b128 v[212:215], v204 offset:0
	ds_read_b128 v[216:219], v204 offset:2048
	ds_read_b128 v[220:223], v204 offset:4096
	ds_read_b128 v[224:227], v204 offset:6144
	ds_read_b128 v[228:231], v205 offset:0
	ds_read_b128 v[232:235], v205 offset:2048
	ds_read_b128 v[236:239], v205 offset:4096
	ds_read_b128 v[240:243], v205 offset:6144
	s_add_u32 m0, s76, 0x18000
	s_nop 0
	global_load_lds_dwordx4 v196, s[68:69]
	s_add_u32 m0, s76, 0x1a000
	s_nop 0
	global_load_lds_dwordx4 v197, s[68:69]
	s_add_u32 m0, s76, 0x1c000
	s_nop 0
	global_load_lds_dwordx4 v198, s[68:69]
	s_add_u32 m0, s76, 0x1e000
	s_nop 0
	global_load_lds_dwordx4 v199, s[68:69]
	s_add_u32 m0, s76, 0x20000
	s_nop 0
	global_load_lds_dwordx4 v196, s[70:71]
	s_add_u32 m0, s76, 0x22000
	s_nop 0
	global_load_lds_dwordx4 v197, s[70:71]
	s_add_u32 s68, s68, 0x80
	s_addc_u32 s69, s69, 0
	s_add_u32 s70, s70, 0x80
	s_addc_u32 s71, s71, 0
	s_waitcnt lgkmcnt(0)
	s_barrier
	v_mfma_f32_16x16x32_bf16 v[2:5], v[146:149], v[130:133], v[2:5]
	v_mfma_f32_16x16x32_bf16 v[6:9], v[150:153], v[130:133], v[6:9]
	v_mfma_f32_16x16x32_bf16 v[10:13], v[154:157], v[130:133], v[10:13]
	v_mfma_f32_16x16x32_bf16 v[14:17], v[158:161], v[130:133], v[14:17]
	v_mfma_f32_16x16x32_bf16 v[18:21], v[146:149], v[134:137], v[18:21]
	v_mfma_f32_16x16x32_bf16 v[22:25], v[150:153], v[134:137], v[22:25]
	v_mfma_f32_16x16x32_bf16 v[26:29], v[154:157], v[134:137], v[26:29]
	v_mfma_f32_16x16x32_bf16 v[30:33], v[158:161], v[134:137], v[30:33]
	v_mfma_f32_16x16x32_bf16 v[34:37], v[146:149], v[138:141], v[34:37]
	v_mfma_f32_16x16x32_bf16 v[38:41], v[150:153], v[138:141], v[38:41]
	v_mfma_f32_16x16x32_bf16 v[42:45], v[154:157], v[138:141], v[42:45]
	v_mfma_f32_16x16x32_bf16 v[46:49], v[158:161], v[138:141], v[46:49]
	v_mfma_f32_16x16x32_bf16 v[50:53], v[146:149], v[142:145], v[50:53]
	v_mfma_f32_16x16x32_bf16 v[54:57], v[150:153], v[142:145], v[54:57]
	v_mfma_f32_16x16x32_bf16 v[58:61], v[154:157], v[142:145], v[58:61]
	v_mfma_f32_16x16x32_bf16 v[62:65], v[158:161], v[142:145], v[62:65]
	v_mfma_f32_16x16x32_bf16 v[2:5], v[228:231], v[212:215], v[2:5]
	v_mfma_f32_16x16x32_bf16 v[6:9], v[232:235], v[212:215], v[6:9]
	v_mfma_f32_16x16x32_bf16 v[10:13], v[236:239], v[212:215], v[10:13]
	v_mfma_f32_16x16x32_bf16 v[14:17], v[240:243], v[212:215], v[14:17]
	v_mfma_f32_16x16x32_bf16 v[18:21], v[228:231], v[216:219], v[18:21]
	v_mfma_f32_16x16x32_bf16 v[22:25], v[232:235], v[216:219], v[22:25]
	v_mfma_f32_16x16x32_bf16 v[26:29], v[236:239], v[216:219], v[26:29]
	v_mfma_f32_16x16x32_bf16 v[30:33], v[240:243], v[216:219], v[30:33]
	v_mfma_f32_16x16x32_bf16 v[34:37], v[228:231], v[220:223], v[34:37]
	v_mfma_f32_16x16x32_bf16 v[38:41], v[232:235], v[220:223], v[38:41]
	v_mfma_f32_16x16x32_bf16 v[42:45], v[236:239], v[220:223], v[42:45]
	v_mfma_f32_16x16x32_bf16 v[46:49], v[240:243], v[220:223], v[46:49]
	v_mfma_f32_16x16x32_bf16 v[50:53], v[228:231], v[224:227], v[50:53]
	v_mfma_f32_16x16x32_bf16 v[54:57], v[232:235], v[224:227], v[54:57]
	v_mfma_f32_16x16x32_bf16 v[58:61], v[236:239], v[224:227], v[58:61]
	v_mfma_f32_16x16x32_bf16 v[62:65], v[240:243], v[224:227], v[62:65]
	s_waitcnt vmcnt(6)
	s_barrier
	v_add_u32_e32 v204, 0xc000, v200
	v_add_u32_e32 v205, 0xc000, v202
	ds_read_b128 v[130:133], v204 offset:0
	ds_read_b128 v[134:137], v204 offset:2048
	ds_read_b128 v[138:141], v204 offset:4096
	ds_read_b128 v[142:145], v204 offset:6144
	ds_read_b128 v[146:149], v205 offset:0
	ds_read_b128 v[150:153], v205 offset:2048
	ds_read_b128 v[154:157], v205 offset:4096
	ds_read_b128 v[158:161], v205 offset:6144
	v_add_u32_e32 v204, 0xc000, v201
	v_add_u32_e32 v205, 0xc000, v203
	ds_read_b128 v[212:215], v204 offset:0
	ds_read_b128 v[216:219], v204 offset:2048
	ds_read_b128 v[220:223], v204 offset:4096
	ds_read_b128 v[224:227], v204 offset:6144
	ds_read_b128 v[228:231], v205 offset:0
	ds_read_b128 v[232:235], v205 offset:2048
	ds_read_b128 v[236:239], v205 offset:4096
	ds_read_b128 v[240:243], v205 offset:6144
	s_add_u32 m0, s76, 0x0
	s_nop 0
	global_load_lds_dwordx4 v196, s[68:69]
	s_add_u32 m0, s76, 0x2000
	s_nop 0
	global_load_lds_dwordx4 v197, s[68:69]
	s_add_u32 m0, s76, 0x4000
	s_nop 0
	global_load_lds_dwordx4 v198, s[68:69]
	s_add_u32 m0, s76, 0x6000
	s_nop 0
	global_load_lds_dwordx4 v199, s[68:69]
	s_add_u32 m0, s76, 0x8000
	s_nop 0
	global_load_lds_dwordx4 v196, s[70:71]
	s_add_u32 m0, s76, 0xa000
	s_nop 0
	global_load_lds_dwordx4 v197, s[70:71]
	s_add_u32 s68, s68, 0x80
	s_addc_u32 s69, s69, 0
	s_add_u32 s70, s70, 0x80
	s_addc_u32 s71, s71, 0
	s_waitcnt lgkmcnt(0)
	s_barrier
	v_mfma_f32_16x16x32_bf16 v[2:5], v[146:149], v[130:133], v[2:5]
	v_mfma_f32_16x16x32_bf16 v[6:9], v[150:153], v[130:133], v[6:9]
	v_mfma_f32_16x16x32_bf16 v[10:13], v[154:157], v[130:133], v[10:13]
	v_mfma_f32_16x16x32_bf16 v[14:17], v[158:161], v[130:133], v[14:17]
	v_mfma_f32_16x16x32_bf16 v[18:21], v[146:149], v[134:137], v[18:21]
	v_mfma_f32_16x16x32_bf16 v[22:25], v[150:153], v[134:137], v[22:25]
	v_mfma_f32_16x16x32_bf16 v[26:29], v[154:157], v[134:137], v[26:29]
	v_mfma_f32_16x16x32_bf16 v[30:33], v[158:161], v[134:137], v[30:33]
	v_mfma_f32_16x16x32_bf16 v[34:37], v[146:149], v[138:141], v[34:37]
	v_mfma_f32_16x16x32_bf16 v[38:41], v[150:153], v[138:141], v[38:41]
	v_mfma_f32_16x16x32_bf16 v[42:45], v[154:157], v[138:141], v[42:45]
	v_mfma_f32_16x16x32_bf16 v[46:49], v[158:161], v[138:141], v[46:49]
	v_mfma_f32_16x16x32_bf16 v[50:53], v[146:149], v[142:145], v[50:53]
	v_mfma_f32_16x16x32_bf16 v[54:57], v[150:153], v[142:145], v[54:57]
	v_mfma_f32_16x16x32_bf16 v[58:61], v[154:157], v[142:145], v[58:61]
	v_mfma_f32_16x16x32_bf16 v[62:65], v[158:161], v[142:145], v[62:65]
	v_mfma_f32_16x16x32_bf16 v[2:5], v[228:231], v[212:215], v[2:5]
	v_mfma_f32_16x16x32_bf16 v[6:9], v[232:235], v[212:215], v[6:9]
	v_mfma_f32_16x16x32_bf16 v[10:13], v[236:239], v[212:215], v[10:13]
	v_mfma_f32_16x16x32_bf16 v[14:17], v[240:243], v[212:215], v[14:17]
	v_mfma_f32_16x16x32_bf16 v[18:21], v[228:231], v[216:219], v[18:21]
	v_mfma_f32_16x16x32_bf16 v[22:25], v[232:235], v[216:219], v[22:25]
	v_mfma_f32_16x16x32_bf16 v[26:29], v[236:239], v[216:219], v[26:29]
	v_mfma_f32_16x16x32_bf16 v[30:33], v[240:243], v[216:219], v[30:33]
	v_mfma_f32_16x16x32_bf16 v[34:37], v[228:231], v[220:223], v[34:37]
	v_mfma_f32_16x16x32_bf16 v[38:41], v[232:235], v[220:223], v[38:41]
	v_mfma_f32_16x16x32_bf16 v[42:45], v[236:239], v[220:223], v[42:45]
	v_mfma_f32_16x16x32_bf16 v[46:49], v[240:243], v[220:223], v[46:49]
	v_mfma_f32_16x16x32_bf16 v[50:53], v[228:231], v[224:227], v[50:53]
	v_mfma_f32_16x16x32_bf16 v[54:57], v[232:235], v[224:227], v[54:57]
	v_mfma_f32_16x16x32_bf16 v[58:61], v[236:239], v[224:227], v[58:61]
	v_mfma_f32_16x16x32_bf16 v[62:65], v[240:243], v[224:227], v[62:65]
	s_waitcnt vmcnt(6)
	s_barrier
	v_add_u32_e32 v204, 0x18000, v200
	v_add_u32_e32 v205, 0x18000, v202
	ds_read_b128 v[130:133], v204 offset:0
	ds_read_b128 v[134:137], v204 offset:2048
	ds_read_b128 v[138:141], v204 offset:4096
	ds_read_b128 v[142:145], v204 offset:6144
	ds_read_b128 v[146:149], v205 offset:0
	ds_read_b128 v[150:153], v205 offset:2048
	ds_read_b128 v[154:157], v205 offset:4096
	ds_read_b128 v[158:161], v205 offset:6144
	v_add_u32_e32 v204, 0x18000, v201
	v_add_u32_e32 v205, 0x18000, v203
	ds_read_b128 v[212:215], v204 offset:0
	ds_read_b128 v[216:219], v204 offset:2048
	ds_read_b128 v[220:223], v204 offset:4096
	ds_read_b128 v[224:227], v204 offset:6144
	ds_read_b128 v[228:231], v205 offset:0
	ds_read_b128 v[232:235], v205 offset:2048
	ds_read_b128 v[236:239], v205 offset:4096
	ds_read_b128 v[240:243], v205 offset:6144
	s_waitcnt lgkmcnt(0)
	s_barrier
	v_mfma_f32_16x16x32_bf16 v[2:5], v[146:149], v[130:133], v[2:5]
	v_mfma_f32_16x16x32_bf16 v[6:9], v[150:153], v[130:133], v[6:9]
	v_mfma_f32_16x16x32_bf16 v[10:13], v[154:157], v[130:133], v[10:13]
	v_mfma_f32_16x16x32_bf16 v[14:17], v[158:161], v[130:133], v[14:17]
	v_mfma_f32_16x16x32_bf16 v[18:21], v[146:149], v[134:137], v[18:21]
	v_mfma_f32_16x16x32_bf16 v[22:25], v[150:153], v[134:137], v[22:25]
	v_mfma_f32_16x16x32_bf16 v[26:29], v[154:157], v[134:137], v[26:29]
	v_mfma_f32_16x16x32_bf16 v[30:33], v[158:161], v[134:137], v[30:33]
	v_mfma_f32_16x16x32_bf16 v[34:37], v[146:149], v[138:141], v[34:37]
	v_mfma_f32_16x16x32_bf16 v[38:41], v[150:153], v[138:141], v[38:41]
	v_mfma_f32_16x16x32_bf16 v[42:45], v[154:157], v[138:141], v[42:45]
	v_mfma_f32_16x16x32_bf16 v[46:49], v[158:161], v[138:141], v[46:49]
	v_mfma_f32_16x16x32_bf16 v[50:53], v[146:149], v[142:145], v[50:53]
	v_mfma_f32_16x16x32_bf16 v[54:57], v[150:153], v[142:145], v[54:57]
	v_mfma_f32_16x16x32_bf16 v[58:61], v[154:157], v[142:145], v[58:61]
	v_mfma_f32_16x16x32_bf16 v[62:65], v[158:161], v[142:145], v[62:65]
	v_mfma_f32_16x16x32_bf16 v[2:5], v[228:231], v[212:215], v[2:5]
	v_mfma_f32_16x16x32_bf16 v[6:9], v[232:235], v[212:215], v[6:9]
	v_mfma_f32_16x16x32_bf16 v[10:13], v[236:239], v[212:215], v[10:13]
	v_mfma_f32_16x16x32_bf16 v[14:17], v[240:243], v[212:215], v[14:17]
	v_mfma_f32_16x16x32_bf16 v[18:21], v[228:231], v[216:219], v[18:21]
	v_mfma_f32_16x16x32_bf16 v[22:25], v[232:235], v[216:219], v[22:25]
	v_mfma_f32_16x16x32_bf16 v[26:29], v[236:239], v[216:219], v[26:29]
	v_mfma_f32_16x16x32_bf16 v[30:33], v[240:243], v[216:219], v[30:33]
	v_mfma_f32_16x16x32_bf16 v[34:37], v[228:231], v[220:223], v[34:37]
	v_mfma_f32_16x16x32_bf16 v[38:41], v[232:235], v[220:223], v[38:41]
	v_mfma_f32_16x16x32_bf16 v[42:45], v[236:239], v[220:223], v[42:45]
	v_mfma_f32_16x16x32_bf16 v[46:49], v[240:243], v[220:223], v[46:49]
	v_mfma_f32_16x16x32_bf16 v[50:53], v[228:231], v[224:227], v[50:53]
	v_mfma_f32_16x16x32_bf16 v[54:57], v[232:235], v[224:227], v[54:57]
	v_mfma_f32_16x16x32_bf16 v[58:61], v[236:239], v[224:227], v[58:61]
	v_mfma_f32_16x16x32_bf16 v[62:65], v[240:243], v[224:227], v[62:65]
	s_waitcnt vmcnt(0)
	s_barrier
	v_add_u32_e32 v204, 0x0, v200
	v_add_u32_e32 v205, 0x0, v202
	ds_read_b128 v[130:133], v204 offset:0
	ds_read_b128 v[134:137], v204 offset:2048
	ds_read_b128 v[138:141], v204 offset:4096
	ds_read_b128 v[142:145], v204 offset:6144
	ds_read_b128 v[146:149], v205 offset:0
	ds_read_b128 v[150:153], v205 offset:2048
	ds_read_b128 v[154:157], v205 offset:4096
	ds_read_b128 v[158:161], v205 offset:6144
	v_add_u32_e32 v204, 0x0, v201
	v_add_u32_e32 v205, 0x0, v203
	ds_read_b128 v[212:215], v204 offset:0
	ds_read_b128 v[216:219], v204 offset:2048
	ds_read_b128 v[220:223], v204 offset:4096
	ds_read_b128 v[224:227], v204 offset:6144
	ds_read_b128 v[228:231], v205 offset:0
	ds_read_b128 v[232:235], v205 offset:2048
	ds_read_b128 v[236:239], v205 offset:4096
	ds_read_b128 v[240:243], v205 offset:6144
	s_waitcnt lgkmcnt(0)
	s_barrier
	v_mfma_f32_16x16x32_bf16 v[2:5], v[146:149], v[130:133], v[2:5]
	v_mfma_f32_16x16x32_bf16 v[6:9], v[150:153], v[130:133], v[6:9]
	v_mfma_f32_16x16x32_bf16 v[10:13], v[154:157], v[130:133], v[10:13]
	v_mfma_f32_16x16x32_bf16 v[14:17], v[158:161], v[130:133], v[14:17]
	v_mfma_f32_16x16x32_bf16 v[18:21], v[146:149], v[134:137], v[18:21]
	v_mfma_f32_16x16x32_bf16 v[22:25], v[150:153], v[134:137], v[22:25]
	v_mfma_f32_16x16x32_bf16 v[26:29], v[154:157], v[134:137], v[26:29]
	v_mfma_f32_16x16x32_bf16 v[30:33], v[158:161], v[134:137], v[30:33]
	v_mfma_f32_16x16x32_bf16 v[34:37], v[146:149], v[138:141], v[34:37]
	v_mfma_f32_16x16x32_bf16 v[38:41], v[150:153], v[138:141], v[38:41]
	v_mfma_f32_16x16x32_bf16 v[42:45], v[154:157], v[138:141], v[42:45]
	v_mfma_f32_16x16x32_bf16 v[46:49], v[158:161], v[138:141], v[46:49]
	v_mfma_f32_16x16x32_bf16 v[50:53], v[146:149], v[142:145], v[50:53]
	v_mfma_f32_16x16x32_bf16 v[54:57], v[150:153], v[142:145], v[54:57]
	v_mfma_f32_16x16x32_bf16 v[58:61], v[154:157], v[142:145], v[58:61]
	v_mfma_f32_16x16x32_bf16 v[62:65], v[158:161], v[142:145], v[62:65]
	v_mfma_f32_16x16x32_bf16 v[2:5], v[228:231], v[212:215], v[2:5]
	v_mfma_f32_16x16x32_bf16 v[6:9], v[232:235], v[212:215], v[6:9]
	v_mfma_f32_16x16x32_bf16 v[10:13], v[236:239], v[212:215], v[10:13]
	v_mfma_f32_16x16x32_bf16 v[14:17], v[240:243], v[212:215], v[14:17]
	v_mfma_f32_16x16x32_bf16 v[18:21], v[228:231], v[216:219], v[18:21]
	v_mfma_f32_16x16x32_bf16 v[22:25], v[232:235], v[216:219], v[22:25]
	v_mfma_f32_16x16x32_bf16 v[26:29], v[236:239], v[216:219], v[26:29]
	v_mfma_f32_16x16x32_bf16 v[30:33], v[240:243], v[216:219], v[30:33]
	v_mfma_f32_16x16x32_bf16 v[34:37], v[228:231], v[220:223], v[34:37]
	v_mfma_f32_16x16x32_bf16 v[38:41], v[232:235], v[220:223], v[38:41]
	v_mfma_f32_16x16x32_bf16 v[42:45], v[236:239], v[220:223], v[42:45]
	v_mfma_f32_16x16x32_bf16 v[46:49], v[240:243], v[220:223], v[46:49]
	v_mfma_f32_16x16x32_bf16 v[50:53], v[228:231], v[224:227], v[50:53]
	v_mfma_f32_16x16x32_bf16 v[54:57], v[232:235], v[224:227], v[54:57]
	v_mfma_f32_16x16x32_bf16 v[58:61], v[236:239], v[224:227], v[58:61]
	v_mfma_f32_16x16x32_bf16 v[62:65], v[240:243], v[224:227], v[62:65]
	s_barrier
	s_branch .Lop_join
